# norm_ctx load hoist at matched placement: 36 bytes of s_nop padding after the loop keep every later loop head at the same byte phase as the previous best
# speedup vs baseline: 1.0068x; 1.0014x over previous
; __device__ __forceinline__ void norm_ctx(const Ctx& X, const float* ctx, const float* P, const float* gate8, const float* gain, const float* mod8, int si, bf16_t* HN) {
;     const float* sh = mod8 + si * 1024; const float* scl = sh + 1024;
;     for (int r = X.gw; r < MC; r += X.NGW) {
;         f32x4 v[4]; float s = 0.f;
; #pragma unroll
;         for (int j = 0; j < 4; ++j) { const int c = (X.lane + 64 * j) * 4; const size_t o = (size_t)r * D + c;
;             const f32x4 p = (*(const f32x4*)(P + o) + *(const f32x4*)(P + (size_t)MC * D + o)) + (*(const f32x4*)(P + (size_t)2 * MC * D + o) + *(const f32x4*)(P + (size_t)3 * MC * D + o));
;             v[j] = *(const f32x4*)(ctx + o) + *(const f32x4*)(gate8 + c) * 0.5f * p; s += (v[j].x * v[j].x + v[j].y * v[j].y) + (v[j].z * v[j].z + v[j].w * v[j].w); }
.LBB0_422:
	global_load_dwordx4 v[208:211], v[16:17], off
	global_load_dwordx4 v[212:215], v[18:19], off
	global_load_dwordx4 v[216:219], v[20:21], off
	global_load_dwordx4 v[220:223], v[22:23], off
	global_load_dwordx4 v[224:227], v[24:25], off
	global_load_dwordx4 v[228:231], v[26:27], off
	global_load_dwordx4 v[232:235], v[28:29], off
	global_load_dwordx4 v[236:239], v[30:31], off
	global_load_dwordx4 v[240:243], v[32:33], off
	v_lshl_add_u64 v[120:121], s[0:1], 0, v[0:1]
	v_add_co_u32_e32 v100, vcc, 0x17400000, v120
	v_lshl_add_u64 v[84:85], s[6:7], 0, v[0:1]
	s_nop 0
	v_addc_co_u32_e32 v101, vcc, 0, v121, vcc
	v_add_co_u32_e32 v116, vcc, 0x17c00000, v120
	global_load_dwordx4 v[44:47], v[2:3], off
	global_load_dwordx4 v[48:51], v[4:5], off
	global_load_dwordx4 v[52:55], v[6:7], off
	global_load_dwordx4 v[56:59], v[8:9], off
	v_addc_co_u32_e32 v117, vcc, 0, v121, vcc
	v_add_co_u32_e32 v132, vcc, 0x18400000, v120
	global_load_dwordx4 v[60:63], v[10:11], off
	global_load_dwordx4 v[64:67], v[12:13], off
	global_load_dwordx4 v[68:71], v[14:15], off
	v_addc_co_u32_e32 v133, vcc, 0, v121, vcc
	v_add_co_u32_e32 v148, vcc, 0x18c00000, v120
	global_load_dwordx4 v[72:75], v[84:85], off
	global_load_dwordx4 v[76:79], v[84:85], off offset:1024
	global_load_dwordx4 v[80:83], v[84:85], off offset:2048
	s_nop 0
	global_load_dwordx4 v[84:87], v[84:85], off offset:3072
	v_addc_co_u32_e32 v149, vcc, 0, v121, vcc
	global_load_dwordx4 v[88:91], v[100:101], off
	global_load_dwordx4 v[92:95], v[100:101], off offset:1024
	global_load_dwordx4 v[96:99], v[100:101], off offset:2048
	s_nop 0
	global_load_dwordx4 v[100:103], v[100:101], off offset:3072
	s_nop 0
	global_load_dwordx4 v[104:107], v[116:117], off
	global_load_dwordx4 v[108:111], v[116:117], off offset:1024
	global_load_dwordx4 v[112:115], v[116:117], off offset:2048
	s_nop 0
	global_load_dwordx4 v[116:119], v[116:117], off offset:3072
	s_nop 0
	global_load_dwordx4 v[120:123], v[132:133], off
	global_load_dwordx4 v[124:127], v[132:133], off offset:1024
	global_load_dwordx4 v[128:131], v[132:133], off offset:2048
	s_nop 0
	global_load_dwordx4 v[132:135], v[132:133], off offset:3072
	s_nop 0
	global_load_dwordx4 v[136:139], v[148:149], off
	global_load_dwordx4 v[140:143], v[148:149], off offset:1024
	global_load_dwordx4 v[144:147], v[148:149], off offset:2048
	s_nop 0
	global_load_dwordx4 v[148:151], v[148:149], off offset:3072
	s_add_i32 s10, s8, 0x8000
	s_ashr_i32 s11, s10, 31
	s_lshl_b64 s[10:11], s[10:11], 11
	v_lshl_add_u64 v[152:153], v[34:35], 0, s[10:11]
	s_add_i32 s8, s8, s20
	s_add_u32 s0, s0, s4
	s_addc_u32 s1, s1, s5
	s_add_u32 s6, s6, s4
	s_addc_u32 s7, s7, s5
	s_cmpk_lt_i32 s8, 0x800
	s_waitcnt vmcnt(26)
	v_pk_mul_f32 v[46:47], v[46:47], 0.5 op_sel_hi:[1,0]
	v_pk_mul_f32 v[44:45], v[44:45], 0.5 op_sel_hi:[1,0]
	s_waitcnt vmcnt(25)
	v_pk_mul_f32 v[50:51], v[50:51], 0.5 op_sel_hi:[1,0]
	v_pk_mul_f32 v[48:49], v[48:49], 0.5 op_sel_hi:[1,0]
	s_waitcnt vmcnt(24)
	v_pk_mul_f32 v[54:55], v[54:55], 0.5 op_sel_hi:[1,0]
	v_pk_mul_f32 v[52:53], v[52:53], 0.5 op_sel_hi:[1,0]
	s_waitcnt vmcnt(23)
	v_pk_mul_f32 v[56:57], v[56:57], 0.5 op_sel_hi:[1,0]
	v_pk_mul_f32 v[58:59], v[58:59], 0.5 op_sel_hi:[1,0]
	s_waitcnt vmcnt(21)
	v_pk_add_f32 v[64:65], v[64:65], 1.0 op_sel_hi:[1,0]
	v_pk_add_f32 v[66:67], v[66:67], 1.0 op_sel_hi:[1,0]
	s_waitcnt vmcnt(11)
	v_pk_add_f32 v[90:91], v[90:91], v[106:107]
	v_pk_add_f32 v[88:89], v[88:89], v[104:105]
	s_waitcnt vmcnt(10)
	v_pk_add_f32 v[94:95], v[94:95], v[110:111]
	v_pk_add_f32 v[92:93], v[92:93], v[108:109]
	s_waitcnt vmcnt(3)
	v_pk_add_f32 v[104:105], v[122:123], v[138:139]
	v_pk_add_f32 v[106:107], v[120:121], v[136:137]
	s_waitcnt vmcnt(2)
	v_pk_add_f32 v[108:109], v[126:127], v[142:143]
	v_pk_add_f32 v[110:111], v[124:125], v[140:141]
	v_pk_add_f32 v[98:99], v[98:99], v[114:115]
	v_pk_add_f32 v[96:97], v[96:97], v[112:113]
	s_waitcnt vmcnt(1)
	v_pk_add_f32 v[112:113], v[130:131], v[146:147]
	v_pk_add_f32 v[114:115], v[128:129], v[144:145]
	v_pk_add_f32 v[90:91], v[90:91], v[104:105]
	v_pk_add_f32 v[88:89], v[88:89], v[106:107]
	v_pk_add_f32 v[94:95], v[94:95], v[108:109]
	v_pk_add_f32 v[92:93], v[92:93], v[110:111]
	v_pk_add_f32 v[102:103], v[102:103], v[118:119]
	v_pk_add_f32 v[100:101], v[100:101], v[116:117]
	s_waitcnt vmcnt(0)
; __device__ __forceinline__ unsigned cvt_pk_bf16(float lo, float hi) { unsigned r; asm("v_cvt_pk_bf16_f32 %0, %1, %2" : "=v"(r) : "v"(lo), "v"(hi)); return r; }
; __device__ __forceinline__ void norm_ctx(const Ctx& X, const float* ctx, const float* P, const float* gate8, const float* gain, const float* mod8, int si, bf16_t* HN) {
;     ...
;         const float rstd = rsqrtf(wave_sum(s) * (1.0f / 1024.0f) + 1e-6f);
; #pragma unroll
;         for (int j = 0; j < 4; ++j) { const int c = (X.lane + 64 * j) * 4; const f32x4 gn = *(const f32x4*)(gain + c), a = *(const f32x4*)(scl + c), b = *(const f32x4*)(sh + c);
;             const f32x4 o = v[j] * rstd * gn * (a + 1.0f) + b; u32x2 w; w.x = cvt_pk_bf16(o.x, o.y); w.y = cvt_pk_bf16(o.z, o.w); *(u32x2*)(HN + (size_t)(MX + r) * D + c) = w; }
;     }
	v_pk_add_f32 v[118:119], v[132:133], v[148:149]
	v_pk_add_f32 v[98:99], v[98:99], v[112:113]
	v_pk_add_f32 v[96:97], v[96:97], v[114:115]
	v_pk_fma_f32 v[46:47], v[90:91], v[46:47], v[74:75]
	v_pk_fma_f32 v[44:45], v[88:89], v[44:45], v[72:73]
	v_pk_fma_f32 v[72:73], v[94:95], v[50:51], v[78:79]
	v_pk_fma_f32 v[74:75], v[92:93], v[48:49], v[76:77]
	v_pk_add_f32 v[116:117], v[134:135], v[150:151]
	v_pk_add_f32 v[100:101], v[100:101], v[118:119]
	v_pk_fma_f32 v[76:77], v[98:99], v[54:55], v[82:83]
	v_pk_fma_f32 v[78:79], v[96:97], v[52:53], v[80:81]
	v_pk_mul_f32 v[48:49], v[46:47], v[46:47]
	v_pk_mul_f32 v[50:51], v[44:45], v[44:45]
	v_pk_mul_f32 v[52:53], v[72:73], v[72:73]
	v_pk_mul_f32 v[54:55], v[74:75], v[74:75]
	v_pk_add_f32 v[102:103], v[102:103], v[116:117]
	v_pk_fma_f32 v[56:57], v[100:101], v[56:57], v[84:85]
	v_pk_mov_b32 v[84:85], v[50:51], v[48:49] op_sel:[1,0]
	v_mov_b32_e32 v51, v49
	v_pk_mov_b32 v[48:49], v[54:55], v[52:53] op_sel:[1,0]
	v_mov_b32_e32 v55, v53
	v_pk_fma_f32 v[58:59], v[102:103], v[58:59], v[86:87]
	v_mul_f32_e32 v83, v57, v57
	v_mul_f32_e32 v80, v79, v79
	v_mul_f32_e32 v82, v77, v77
	v_pk_add_f32 v[50:51], v[84:85], v[50:51]
	v_pk_add_f32 v[48:49], v[48:49], v[54:55]
	v_mul_f32_e32 v43, v56, v56
	v_mul_f32_e32 v86, v58, v58
	v_mul_f32_e32 v87, v59, v59
	v_pk_fma_f32 v[52:53], v[78:79], v[78:79], v[80:81] op_sel_hi:[1,1,0]
	v_pk_fma_f32 v[80:81], v[76:77], v[76:77], v[82:83] op_sel_hi:[1,1,0]
	v_pk_add_f32 v[50:51], v[50:51], v[50:51] op_sel:[0,1] op_sel_hi:[1,0]
	v_pk_add_f32 v[48:49], v[48:49], v[48:49] op_sel:[0,1] op_sel_hi:[1,0]
	v_mov_b32_e32 v53, v86
	v_mov_b32_e32 v81, v87
	v_mov_b32_e32 v51, v43
	v_mov_b32_e32 v49, v83
	v_pk_add_f32 v[52:53], v[52:53], v[80:81]
	v_pk_add_f32 v[48:49], v[50:51], v[48:49]
	s_nop 0
	v_pk_add_f32 v[48:49], v[48:49], v[52:53]
	s_nop 0
	v_add_f32_e32 v43, v48, v49
	ds_bpermute_b32 v48, v36, v43
	s_waitcnt lgkmcnt(0)
	v_add_f32_e32 v43, v43, v48
	ds_bpermute_b32 v48, v37, v43
	s_waitcnt lgkmcnt(0)
	v_add_f32_e32 v43, v43, v48
	ds_bpermute_b32 v48, v38, v43
	s_waitcnt lgkmcnt(0)
	v_add_f32_e32 v43, v43, v48
	ds_bpermute_b32 v48, v39, v43
	s_waitcnt lgkmcnt(0)
	v_add_f32_e32 v43, v43, v48
	ds_bpermute_b32 v48, v40, v43
	s_waitcnt lgkmcnt(0)
	v_add_f32_e32 v43, v43, v48
	ds_bpermute_b32 v48, v41, v43
	s_waitcnt lgkmcnt(0)
	v_add_f32_e32 v43, v43, v48
	v_fmamk_f32 v43, v43, 0x3a800000, v42
	v_mul_f32_e32 v48, 0x4b800000, v43
	v_cmp_gt_f32_e32 vcc, s9, v43
	s_nop 1
	v_cndmask_b32_e32 v43, v43, v48, vcc
	v_rsq_f32_e32 v43, v43
	s_nop 0
	v_mul_f32_e32 v48, 0x45800000, v43
	v_cndmask_b32_e32 v80, v43, v48, vcc
	v_pk_mul_f32 v[44:45], v[44:45], v[80:81] op_sel_hi:[1,0]
	v_pk_mul_f32 v[46:47], v[46:47], v[80:81] op_sel_hi:[1,0]
	v_pk_mul_f32 v[44:45], v[60:61], v[44:45]
	v_pk_mul_f32 v[46:47], v[62:63], v[46:47]
	v_pk_fma_f32 v[44:45], v[64:65], v[44:45], v[68:69]
	v_pk_fma_f32 v[46:47], v[66:67], v[46:47], v[70:71]
	v_cvt_pk_bf16_f32 v44, v44, v45
	v_pk_mul_f32 v[62:63], v[74:75], v[80:81] op_sel_hi:[1,0]
	v_cvt_pk_bf16_f32 v45, v46, v47
	global_store_dwordx2 v[152:153], v[44:45], off
	s_nop 1
	v_pk_mul_f32 v[60:61], v[72:73], v[80:81] op_sel_hi:[1,0]
	v_pk_mul_f32 v[56:57], v[56:57], v[80:81] op_sel_hi:[1,0]
	v_pk_mul_f32 v[58:59], v[58:59], v[80:81] op_sel_hi:[1,0]
	v_pk_mul_f32 v[44:45], v[208:209], v[62:63]
	v_pk_add_f32 v[48:49], v[212:213], 1.0 op_sel_hi:[1,0]
	v_pk_mul_f32 v[46:47], v[210:211], v[60:61]
	v_pk_add_f32 v[50:51], v[214:215], 1.0 op_sel_hi:[1,0]
	v_pk_fma_f32 v[44:45], v[48:49], v[44:45], v[216:217]
	v_pk_fma_f32 v[46:47], v[50:51], v[46:47], v[218:219]
	v_cvt_pk_bf16_f32 v44, v44, v45
	v_pk_mul_f32 v[62:63], v[78:79], v[80:81] op_sel_hi:[1,0]
	v_cvt_pk_bf16_f32 v45, v46, v47
	global_store_dwordx2 v[152:153], v[44:45], off offset:512
	s_nop 1
	v_pk_mul_f32 v[60:61], v[76:77], v[80:81] op_sel_hi:[1,0]
	v_pk_mul_f32 v[44:45], v[220:221], v[62:63]
	v_pk_add_f32 v[48:49], v[224:225], 1.0 op_sel_hi:[1,0]
	v_pk_mul_f32 v[46:47], v[222:223], v[60:61]
	v_pk_add_f32 v[50:51], v[226:227], 1.0 op_sel_hi:[1,0]
	v_pk_fma_f32 v[44:45], v[48:49], v[44:45], v[228:229]
	v_pk_fma_f32 v[46:47], v[50:51], v[46:47], v[230:231]
	v_cvt_pk_bf16_f32 v44, v44, v45
	s_nop 0
	v_cvt_pk_bf16_f32 v45, v46, v47
	global_store_dwordx2 v[152:153], v[44:45], off offset:1024
	s_nop 1
	v_pk_mul_f32 v[44:45], v[56:57], v[232:233]
	v_pk_add_f32 v[48:49], v[236:237], 1.0 op_sel_hi:[1,0]
	v_pk_mul_f32 v[46:47], v[58:59], v[234:235]
	v_pk_add_f32 v[50:51], v[238:239], 1.0 op_sel_hi:[1,0]
	v_pk_fma_f32 v[44:45], v[44:45], v[48:49], v[240:241]
	v_pk_fma_f32 v[46:47], v[46:47], v[50:51], v[242:243]
	v_cvt_pk_bf16_f32 v44, v44, v45
	s_nop 0
	v_cvt_pk_bf16_f32 v45, v46, v47
	global_store_dwordx2 v[152:153], v[44:45], off offset:1536
	s_cbranch_scc1 .LBB0_422
	s_nop 0
	s_nop 0
	s_nop 0
	s_nop 0
	s_nop 0
	s_nop 0
	s_nop 0
	s_nop 0
	s_nop 0
